# combine pass with three row sets in flight per wave instead of two
# speedup vs baseline: 1.0081x; 1.0033x over previous
.LBB0_236:
	s_mov_b32 s87, s12
	s_lshl_b64 s[4:5], s[86:87], 4
	s_add_u32 s4, s60, s4
	s_addc_u32 s5, s61, s5
	s_load_dwordx4 s[96:99], s[4:5], 0xc0
	s_mov_b64 s[4:5], -1
	s_waitcnt lgkmcnt(0)
	s_ashr_i32 s42, s97, 1
	s_cmp_lt_i32 s96, 3
	s_cbranch_scc1 .LBB0_327
	s_cmp_lt_i32 s96, 4
	s_cbranch_scc1 .LBB0_311
	s_cmp_lt_i32 s96, 5
	s_cbranch_scc1 .LBB0_245
	s_cmp_eq_u32 s96, 5
	s_cbranch_scc0 .LBB0_244
	v_lshrrev_b32_e32 v1, 6, v175
	v_readlane_b32 s3, v253, 4
	v_readfirstlane_b32 s43, v1
	s_nop 3
	s_add_u32 s18, s3, s43
	v_readlane_b32 s4, v254, 18
	v_readlane_b32 s5, v254, 19
	v_readlane_b32 s6, v254, 16
	v_readlane_b32 s7, v254, 17
	s_lshl_b32 s8, s42, 13
	s_add_u32 s4, s4, s8
	s_addc_u32 s5, s5, 0
	s_lshl_b32 s8, s42, 7
	s_add_u32 s6, s6, s8
	s_addc_u32 s7, s7, 0
	v_and_b32_e32 v2, 31, v175
	v_bfe_u32 v3, v175, 5, 1
	s_lshl_b32 s8, s18, 1
	s_and_b32 s8, s8, 6
	v_or_b32_e32 v3, s8, v3
	v_lshlrev_b32_e32 v46, 3, v2
	v_lshl_or_b32 v46, v3, 8, v46
	v_lshlrev_b32_e32 v100, 1, v46
	v_lshrrev_b32_e32 v47, 5, v46
	v_and_b32_e32 v48, 3, v2
	v_lshlrev_b32_e32 v48, 4, v48
	v_lshl_or_b32 v101, v47, 20, v48
	v_lshlrev_b32_e32 v47, 2, v46
	global_load_dwordx4 v[36:39], v47, s[4:5]
	global_load_dwordx4 v[40:43], v47, s[4:5] offset:16
	v_lshrrev_b32_e32 v48, 3, v2
	v_lshl_or_b32 v48, v3, 2, v48
	v_lshlrev_b32_e32 v48, 2, v48
	global_load_dword v44, v48, s[6:7]
	s_lshr_b32 s43, s18, 2
	s_lshl_b32 s3, s43, 12
	s_add_u32 s4, s48, s3
	s_addc_u32 s5, s49, 0
	s_add_u32 s6, s52, s3
	s_addc_u32 s7, s53, 0
	s_add_u32 s8, s50, s3
	s_addc_u32 s9, s51, 0
	s_lshl_b32 s3, s43, 6
	s_add_u32 s14, s46, s3
	s_addc_u32 s15, s47, 0
	s_lshl_b32 s16, s28, 10
	s_lshl_b32 s17, s28, 4
	s_mov_b32 vcc_lo, s8
	s_mov_b32 vcc_hi, s9
	global_load_dwordx4 v[4:7], v100, s[4:5] nt
	global_load_dwordx4 v[8:11], v100, s[6:7] nt
	global_load_dwordx4 v[12:15], v100, vcc
	s_add_u32 s4, s4, s16
	s_addc_u32 s5, s5, 0
	s_add_u32 s6, s6, s16
	s_addc_u32 s7, s7, 0
	s_add_u32 vcc_lo, vcc_lo, s16
	s_addc_u32 vcc_hi, vcc_hi, 0
	global_load_dwordx4 v[20:23], v100, s[4:5] nt
	global_load_dwordx4 v[24:27], v100, s[6:7] nt
	global_load_dwordx4 v[28:31], v100, vcc
	s_add_u32 s4, s4, s16
	s_addc_u32 s5, s5, 0
	s_add_u32 s6, s6, s16
	s_addc_u32 s7, s7, 0
	s_add_u32 vcc_lo, vcc_lo, s16
	s_addc_u32 vcc_hi, vcc_hi, 0
	global_load_dwordx4 v[116:119], v100, s[4:5] nt
	global_load_dwordx4 v[120:123], v100, s[6:7] nt
	global_load_dwordx4 v[124:127], v100, vcc
	s_add_u32 s4, s4, s16
	s_addc_u32 s5, s5, 0
	s_add_u32 s6, s6, s16
	s_addc_u32 s7, s7, 0
	s_add_u32 vcc_lo, vcc_lo, s16
	s_addc_u32 vcc_hi, vcc_hi, 0
	s_waitcnt vmcnt(6)
	v_lshlrev_b32_e32 v46, 16, v12
	v_and_b32_e32 v47, 0xffff0000, v12
	v_lshlrev_b32_e32 v48, 16, v13
	v_and_b32_e32 v49, 0xffff0000, v13
	v_lshlrev_b32_e32 v50, 16, v14
	v_and_b32_e32 v51, 0xffff0000, v14
	v_lshlrev_b32_e32 v52, 16, v15
	v_and_b32_e32 v53, 0xffff0000, v15
	v_mul_f32_e32 v54, 0xbfb8aa3b, v46
	v_mul_f32_e32 v55, 0xbfb8aa3b, v47
	v_mul_f32_e32 v56, 0xbfb8aa3b, v48
	v_mul_f32_e32 v57, 0xbfb8aa3b, v49
	v_mul_f32_e32 v58, 0xbfb8aa3b, v50
	v_mul_f32_e32 v59, 0xbfb8aa3b, v51
	v_mul_f32_e32 v60, 0xbfb8aa3b, v52
	v_mul_f32_e32 v61, 0xbfb8aa3b, v53
	v_exp_f32_e32 v54, v54
	v_exp_f32_e32 v55, v55
	v_exp_f32_e32 v56, v56
	v_exp_f32_e32 v57, v57
	v_exp_f32_e32 v58, v58
	v_exp_f32_e32 v59, v59
	v_exp_f32_e32 v60, v60
	v_exp_f32_e32 v61, v61
	v_lshlrev_b32_e32 v62, 16, v4
	v_and_b32_e32 v63, 0xffff0000, v4
	v_lshlrev_b32_e32 v78, 16, v8
	v_and_b32_e32 v79, 0xffff0000, v8
	v_lshlrev_b32_e32 v64, 16, v5
	v_and_b32_e32 v65, 0xffff0000, v5
	v_lshlrev_b32_e32 v80, 16, v9
	v_and_b32_e32 v81, 0xffff0000, v9
	v_lshlrev_b32_e32 v66, 16, v6
	v_and_b32_e32 v67, 0xffff0000, v6
	v_lshlrev_b32_e32 v82, 16, v10
	v_and_b32_e32 v83, 0xffff0000, v10
	v_lshlrev_b32_e32 v68, 16, v7
	v_and_b32_e32 v69, 0xffff0000, v7
	v_lshlrev_b32_e32 v84, 16, v11
	v_and_b32_e32 v85, 0xffff0000, v11
	v_add_f32_e32 v54, 1.0, v54
	v_add_f32_e32 v55, 1.0, v55
	v_add_f32_e32 v56, 1.0, v56
	v_add_f32_e32 v57, 1.0, v57
	v_add_f32_e32 v58, 1.0, v58
	v_add_f32_e32 v59, 1.0, v59
	v_add_f32_e32 v60, 1.0, v60
	v_add_f32_e32 v61, 1.0, v61
	v_rcp_f32_e32 v54, v54
	v_rcp_f32_e32 v55, v55
	v_rcp_f32_e32 v56, v56
	v_rcp_f32_e32 v57, v57
	v_rcp_f32_e32 v58, v58
	v_rcp_f32_e32 v59, v59
	v_rcp_f32_e32 v60, v60
	v_rcp_f32_e32 v61, v61
	v_pk_add_f32 v[62:63], v[62:63], v[78:79]
	v_pk_add_f32 v[64:65], v[64:65], v[80:81]
	v_pk_add_f32 v[66:67], v[66:67], v[82:83]
	v_pk_add_f32 v[68:69], v[68:69], v[84:85]
	v_pk_mul_f32 v[54:55], v[54:55], v[46:47]
	v_pk_mul_f32 v[56:57], v[56:57], v[48:49]
	v_pk_mul_f32 v[58:59], v[58:59], v[50:51]
	v_pk_mul_f32 v[60:61], v[60:61], v[52:53]
	v_pk_mul_f32 v[62:63], v[62:63], v[54:55]
	v_pk_mul_f32 v[64:65], v[64:65], v[56:57]
	v_pk_mul_f32 v[66:67], v[66:67], v[58:59]
	v_pk_mul_f32 v[68:69], v[68:69], v[60:61]
	v_pk_mul_f32 v[46:47], v[62:63], v[62:63]
	v_pk_mul_f32 v[48:49], v[66:67], v[66:67]
	v_pk_fma_f32 v[46:47], v[64:65], v[64:65], v[46:47]
	v_pk_fma_f32 v[48:49], v[68:69], v[68:69], v[48:49]
	v_pk_add_f32 v[46:47], v[46:47], v[48:49]
	s_nop 0
	v_add_f32_e32 v46, v46, v47
	s_nop 1
	v_add_f32_dpp v46, v46, v46 quad_perm:[1,0,3,2] row_mask:0xf bank_mask:0xf
	s_nop 1
	v_add_f32_dpp v46, v46, v46 quad_perm:[2,3,0,1] row_mask:0xf bank_mask:0xf
	s_nop 1
	v_add_f32_dpp v46, v46, v46 row_half_mirror row_mask:0xf bank_mask:0xf
	s_nop 1
	v_add_f32_dpp v46, v46, v46 row_mirror row_mask:0xf bank_mask:0xf
	s_nop 1
	ds_swizzle_b32 v47, v46 offset:swizzle(SWAP,16)
	s_waitcnt lgkmcnt(0)
	v_add_f32_e32 v46, v46, v47
	v_fmamk_f32 v46, v46, 0x3b800000, v174
	v_rsq_f32_e32 v46, v46
	s_nop 0
	v_pk_mul_f32 v[62:63], v[62:63], v[46:47] op_sel_hi:[1,0]
	v_pk_mul_f32 v[64:65], v[64:65], v[46:47] op_sel_hi:[1,0]
	v_pk_mul_f32 v[66:67], v[66:67], v[46:47] op_sel_hi:[1,0]
	v_pk_mul_f32 v[68:69], v[68:69], v[46:47] op_sel_hi:[1,0]
	v_pk_mul_f32 v[62:63], v[62:63], v[36:37]
	v_pk_mul_f32 v[64:65], v[64:65], v[38:39]
	v_pk_mul_f32 v[66:67], v[66:67], v[40:41]
	v_pk_mul_f32 v[68:69], v[68:69], v[42:43]
	v_cvt_pk_bf16_f32 v88, v62, v63
	v_cvt_pk_bf16_f32 v89, v64, v65
	v_cvt_pk_bf16_f32 v90, v66, v67
	v_cvt_pk_bf16_f32 v91, v68, v69
	global_load_dwordx4 v[4:7], v100, s[4:5] nt
	global_load_dwordx4 v[8:11], v100, s[6:7] nt
	global_load_dwordx4 v[12:15], v100, vcc
	s_add_u32 s4, s4, s16
	s_addc_u32 s5, s5, 0
	s_add_u32 s6, s6, s16
	s_addc_u32 s7, s7, 0
	s_add_u32 vcc_lo, vcc_lo, s16
	s_addc_u32 vcc_hi, vcc_hi, 0
	global_store_dwordx4 v100, v[88:91], s[8:9]
	s_add_u32 s8, s8, s16
	s_addc_u32 s9, s9, 0
	s_add_u32 s18, s18, s28
	s_cmp_lt_u32 s18, s35
	s_cbranch_scc0 .Lc_exit
	s_waitcnt vmcnt(7)
	v_lshlrev_b32_e32 v46, 16, v28
	v_and_b32_e32 v47, 0xffff0000, v28
	v_lshlrev_b32_e32 v48, 16, v29
	v_and_b32_e32 v49, 0xffff0000, v29
	v_lshlrev_b32_e32 v50, 16, v30
	v_and_b32_e32 v51, 0xffff0000, v30
	v_lshlrev_b32_e32 v52, 16, v31
	v_and_b32_e32 v53, 0xffff0000, v31
	v_mul_f32_e32 v54, 0xbfb8aa3b, v46
	v_mul_f32_e32 v55, 0xbfb8aa3b, v47
	v_mul_f32_e32 v56, 0xbfb8aa3b, v48
	v_mul_f32_e32 v57, 0xbfb8aa3b, v49
	v_mul_f32_e32 v58, 0xbfb8aa3b, v50
	v_mul_f32_e32 v59, 0xbfb8aa3b, v51
	v_mul_f32_e32 v60, 0xbfb8aa3b, v52
	v_mul_f32_e32 v61, 0xbfb8aa3b, v53
	v_exp_f32_e32 v54, v54
	v_exp_f32_e32 v55, v55
	v_exp_f32_e32 v56, v56
	v_exp_f32_e32 v57, v57
	v_exp_f32_e32 v58, v58
	v_exp_f32_e32 v59, v59
	v_exp_f32_e32 v60, v60
	v_exp_f32_e32 v61, v61
	v_lshlrev_b32_e32 v62, 16, v20
	v_and_b32_e32 v63, 0xffff0000, v20
	v_lshlrev_b32_e32 v78, 16, v24
	v_and_b32_e32 v79, 0xffff0000, v24
	v_lshlrev_b32_e32 v64, 16, v21
	v_and_b32_e32 v65, 0xffff0000, v21
	v_lshlrev_b32_e32 v80, 16, v25
	v_and_b32_e32 v81, 0xffff0000, v25
	v_lshlrev_b32_e32 v66, 16, v22
	v_and_b32_e32 v67, 0xffff0000, v22
	v_lshlrev_b32_e32 v82, 16, v26
	v_and_b32_e32 v83, 0xffff0000, v26
	v_lshlrev_b32_e32 v68, 16, v23
	v_and_b32_e32 v69, 0xffff0000, v23
	v_lshlrev_b32_e32 v84, 16, v27
	v_and_b32_e32 v85, 0xffff0000, v27
	v_add_f32_e32 v54, 1.0, v54
	v_add_f32_e32 v55, 1.0, v55
	v_add_f32_e32 v56, 1.0, v56
	v_add_f32_e32 v57, 1.0, v57
	v_add_f32_e32 v58, 1.0, v58
	v_add_f32_e32 v59, 1.0, v59
	v_add_f32_e32 v60, 1.0, v60
	v_add_f32_e32 v61, 1.0, v61
	v_rcp_f32_e32 v54, v54
	v_rcp_f32_e32 v55, v55
	v_rcp_f32_e32 v56, v56
	v_rcp_f32_e32 v57, v57
	v_rcp_f32_e32 v58, v58
	v_rcp_f32_e32 v59, v59
	v_rcp_f32_e32 v60, v60
	v_rcp_f32_e32 v61, v61
	v_pk_add_f32 v[62:63], v[62:63], v[78:79]
	v_pk_add_f32 v[64:65], v[64:65], v[80:81]
	v_pk_add_f32 v[66:67], v[66:67], v[82:83]
	v_pk_add_f32 v[68:69], v[68:69], v[84:85]
	v_pk_mul_f32 v[54:55], v[54:55], v[46:47]
	v_pk_mul_f32 v[56:57], v[56:57], v[48:49]
	v_pk_mul_f32 v[58:59], v[58:59], v[50:51]
	v_pk_mul_f32 v[60:61], v[60:61], v[52:53]
	v_pk_mul_f32 v[62:63], v[62:63], v[54:55]
	v_pk_mul_f32 v[64:65], v[64:65], v[56:57]
	v_pk_mul_f32 v[66:67], v[66:67], v[58:59]
	v_pk_mul_f32 v[68:69], v[68:69], v[60:61]
	v_pk_mul_f32 v[46:47], v[62:63], v[62:63]
	v_pk_mul_f32 v[48:49], v[66:67], v[66:67]
	v_pk_fma_f32 v[46:47], v[64:65], v[64:65], v[46:47]
	v_pk_fma_f32 v[48:49], v[68:69], v[68:69], v[48:49]
	v_pk_add_f32 v[46:47], v[46:47], v[48:49]
	s_nop 0
	v_add_f32_e32 v46, v46, v47
	s_nop 1
	v_add_f32_dpp v46, v46, v46 quad_perm:[1,0,3,2] row_mask:0xf bank_mask:0xf
	s_nop 1
	v_add_f32_dpp v46, v46, v46 quad_perm:[2,3,0,1] row_mask:0xf bank_mask:0xf
	s_nop 1
	v_add_f32_dpp v46, v46, v46 row_half_mirror row_mask:0xf bank_mask:0xf
	s_nop 1
	v_add_f32_dpp v46, v46, v46 row_mirror row_mask:0xf bank_mask:0xf
	s_nop 1
	ds_swizzle_b32 v47, v46 offset:swizzle(SWAP,16)
	s_waitcnt lgkmcnt(0)
	v_add_f32_e32 v46, v46, v47
	v_fmamk_f32 v46, v46, 0x3b800000, v174
	v_rsq_f32_e32 v46, v46
	s_nop 0
	v_pk_mul_f32 v[62:63], v[62:63], v[46:47] op_sel_hi:[1,0]
	v_pk_mul_f32 v[64:65], v[64:65], v[46:47] op_sel_hi:[1,0]
	v_pk_mul_f32 v[66:67], v[66:67], v[46:47] op_sel_hi:[1,0]
	v_pk_mul_f32 v[68:69], v[68:69], v[46:47] op_sel_hi:[1,0]
	v_pk_mul_f32 v[62:63], v[62:63], v[36:37]
	v_pk_mul_f32 v[64:65], v[64:65], v[38:39]
	v_pk_mul_f32 v[66:67], v[66:67], v[40:41]
	v_pk_mul_f32 v[68:69], v[68:69], v[42:43]
	v_cvt_pk_bf16_f32 v88, v62, v63
	v_cvt_pk_bf16_f32 v89, v64, v65
	v_cvt_pk_bf16_f32 v90, v66, v67
	v_cvt_pk_bf16_f32 v91, v68, v69
	global_load_dwordx4 v[20:23], v100, s[4:5] nt
	global_load_dwordx4 v[24:27], v100, s[6:7] nt
	global_load_dwordx4 v[28:31], v100, vcc
	s_add_u32 s4, s4, s16
	s_addc_u32 s5, s5, 0
	s_add_u32 s6, s6, s16
	s_addc_u32 s7, s7, 0
	s_add_u32 vcc_lo, vcc_lo, s16
	s_addc_u32 vcc_hi, vcc_hi, 0
	global_store_dwordx4 v100, v[88:91], s[8:9]
	s_add_u32 s8, s8, s16
	s_addc_u32 s9, s9, 0
	s_add_u32 s18, s18, s28
	s_cmp_lt_u32 s18, s35
	s_cbranch_scc0 .Lc_exit
	s_waitcnt vmcnt(8)
	v_lshlrev_b32_e32 v46, 16, v124
	v_and_b32_e32 v47, 0xffff0000, v124
	v_lshlrev_b32_e32 v48, 16, v125
	v_and_b32_e32 v49, 0xffff0000, v125
	v_lshlrev_b32_e32 v50, 16, v126
	v_and_b32_e32 v51, 0xffff0000, v126
	v_lshlrev_b32_e32 v52, 16, v127
	v_and_b32_e32 v53, 0xffff0000, v127
	v_mul_f32_e32 v54, 0xbfb8aa3b, v46
	v_mul_f32_e32 v55, 0xbfb8aa3b, v47
	v_mul_f32_e32 v56, 0xbfb8aa3b, v48
	v_mul_f32_e32 v57, 0xbfb8aa3b, v49
	v_mul_f32_e32 v58, 0xbfb8aa3b, v50
	v_mul_f32_e32 v59, 0xbfb8aa3b, v51
	v_mul_f32_e32 v60, 0xbfb8aa3b, v52
	v_mul_f32_e32 v61, 0xbfb8aa3b, v53
	v_exp_f32_e32 v54, v54
	v_exp_f32_e32 v55, v55
	v_exp_f32_e32 v56, v56
	v_exp_f32_e32 v57, v57
	v_exp_f32_e32 v58, v58
	v_exp_f32_e32 v59, v59
	v_exp_f32_e32 v60, v60
	v_exp_f32_e32 v61, v61
	v_lshlrev_b32_e32 v62, 16, v116
	v_and_b32_e32 v63, 0xffff0000, v116
	v_lshlrev_b32_e32 v78, 16, v120
	v_and_b32_e32 v79, 0xffff0000, v120
	v_lshlrev_b32_e32 v64, 16, v117
	v_and_b32_e32 v65, 0xffff0000, v117
	v_lshlrev_b32_e32 v80, 16, v121
	v_and_b32_e32 v81, 0xffff0000, v121
	v_lshlrev_b32_e32 v66, 16, v118
	v_and_b32_e32 v67, 0xffff0000, v118
	v_lshlrev_b32_e32 v82, 16, v122
	v_and_b32_e32 v83, 0xffff0000, v122
	v_lshlrev_b32_e32 v68, 16, v119
	v_and_b32_e32 v69, 0xffff0000, v119
	v_lshlrev_b32_e32 v84, 16, v123
	v_and_b32_e32 v85, 0xffff0000, v123
	v_add_f32_e32 v54, 1.0, v54
	v_add_f32_e32 v55, 1.0, v55
	v_add_f32_e32 v56, 1.0, v56
	v_add_f32_e32 v57, 1.0, v57
	v_add_f32_e32 v58, 1.0, v58
	v_add_f32_e32 v59, 1.0, v59
	v_add_f32_e32 v60, 1.0, v60
	v_add_f32_e32 v61, 1.0, v61
	v_rcp_f32_e32 v54, v54
	v_rcp_f32_e32 v55, v55
	v_rcp_f32_e32 v56, v56
	v_rcp_f32_e32 v57, v57
	v_rcp_f32_e32 v58, v58
	v_rcp_f32_e32 v59, v59
	v_rcp_f32_e32 v60, v60
	v_rcp_f32_e32 v61, v61
	v_pk_add_f32 v[62:63], v[62:63], v[78:79]
	v_pk_add_f32 v[64:65], v[64:65], v[80:81]
	v_pk_add_f32 v[66:67], v[66:67], v[82:83]
	v_pk_add_f32 v[68:69], v[68:69], v[84:85]
	v_pk_mul_f32 v[54:55], v[54:55], v[46:47]
	v_pk_mul_f32 v[56:57], v[56:57], v[48:49]
	v_pk_mul_f32 v[58:59], v[58:59], v[50:51]
	v_pk_mul_f32 v[60:61], v[60:61], v[52:53]
	v_pk_mul_f32 v[62:63], v[62:63], v[54:55]
	v_pk_mul_f32 v[64:65], v[64:65], v[56:57]
	v_pk_mul_f32 v[66:67], v[66:67], v[58:59]
	v_pk_mul_f32 v[68:69], v[68:69], v[60:61]
	v_pk_mul_f32 v[46:47], v[62:63], v[62:63]
	v_pk_mul_f32 v[48:49], v[66:67], v[66:67]
	v_pk_fma_f32 v[46:47], v[64:65], v[64:65], v[46:47]
	v_pk_fma_f32 v[48:49], v[68:69], v[68:69], v[48:49]
	v_pk_add_f32 v[46:47], v[46:47], v[48:49]
	s_nop 0
	v_add_f32_e32 v46, v46, v47
	s_nop 1
	v_add_f32_dpp v46, v46, v46 quad_perm:[1,0,3,2] row_mask:0xf bank_mask:0xf
	s_nop 1
	v_add_f32_dpp v46, v46, v46 quad_perm:[2,3,0,1] row_mask:0xf bank_mask:0xf
	s_nop 1
	v_add_f32_dpp v46, v46, v46 row_half_mirror row_mask:0xf bank_mask:0xf
	s_nop 1
	v_add_f32_dpp v46, v46, v46 row_mirror row_mask:0xf bank_mask:0xf
	s_nop 1
	ds_swizzle_b32 v47, v46 offset:swizzle(SWAP,16)
	s_waitcnt lgkmcnt(0)
	v_add_f32_e32 v46, v46, v47
	v_fmamk_f32 v46, v46, 0x3b800000, v174
	v_rsq_f32_e32 v46, v46
	s_nop 0
	v_pk_mul_f32 v[62:63], v[62:63], v[46:47] op_sel_hi:[1,0]
	v_pk_mul_f32 v[64:65], v[64:65], v[46:47] op_sel_hi:[1,0]
	v_pk_mul_f32 v[66:67], v[66:67], v[46:47] op_sel_hi:[1,0]
	v_pk_mul_f32 v[68:69], v[68:69], v[46:47] op_sel_hi:[1,0]
	v_pk_mul_f32 v[62:63], v[62:63], v[36:37]
	v_pk_mul_f32 v[64:65], v[64:65], v[38:39]
	v_pk_mul_f32 v[66:67], v[66:67], v[40:41]
	v_pk_mul_f32 v[68:69], v[68:69], v[42:43]
	v_cvt_pk_bf16_f32 v88, v62, v63
	v_cvt_pk_bf16_f32 v89, v64, v65
	v_cvt_pk_bf16_f32 v90, v66, v67
	v_cvt_pk_bf16_f32 v91, v68, v69
	global_load_dwordx4 v[116:119], v100, s[4:5] nt
	global_load_dwordx4 v[120:123], v100, s[6:7] nt
	global_load_dwordx4 v[124:127], v100, vcc
	s_add_u32 s4, s4, s16
	s_addc_u32 s5, s5, 0
	s_add_u32 s6, s6, s16
	s_addc_u32 s7, s7, 0
	s_add_u32 vcc_lo, vcc_lo, s16
	s_addc_u32 vcc_hi, vcc_hi, 0
	global_store_dwordx4 v100, v[88:91], s[8:9]
	s_add_u32 s8, s8, s16
	s_addc_u32 s9, s9, 0
	s_add_u32 s18, s18, s28
	s_cmp_lt_u32 s18, s35
	s_cbranch_scc0 .Lc_exit
.Lc_loop:
	s_waitcnt vmcnt(9)
	v_lshlrev_b32_e32 v46, 16, v12
	v_and_b32_e32 v47, 0xffff0000, v12
	v_lshlrev_b32_e32 v48, 16, v13
	v_and_b32_e32 v49, 0xffff0000, v13
	v_lshlrev_b32_e32 v50, 16, v14
	v_and_b32_e32 v51, 0xffff0000, v14
	v_lshlrev_b32_e32 v52, 16, v15
	v_and_b32_e32 v53, 0xffff0000, v15
	v_mul_f32_e32 v54, 0xbfb8aa3b, v46
	v_mul_f32_e32 v55, 0xbfb8aa3b, v47
	v_mul_f32_e32 v56, 0xbfb8aa3b, v48
	v_mul_f32_e32 v57, 0xbfb8aa3b, v49
	v_mul_f32_e32 v58, 0xbfb8aa3b, v50
	v_mul_f32_e32 v59, 0xbfb8aa3b, v51
	v_mul_f32_e32 v60, 0xbfb8aa3b, v52
	v_mul_f32_e32 v61, 0xbfb8aa3b, v53
	v_exp_f32_e32 v54, v54
	v_exp_f32_e32 v55, v55
	v_exp_f32_e32 v56, v56
	v_exp_f32_e32 v57, v57
	v_exp_f32_e32 v58, v58
	v_exp_f32_e32 v59, v59
	v_exp_f32_e32 v60, v60
	v_exp_f32_e32 v61, v61
	v_lshlrev_b32_e32 v62, 16, v4
	v_and_b32_e32 v63, 0xffff0000, v4
	v_lshlrev_b32_e32 v78, 16, v8
	v_and_b32_e32 v79, 0xffff0000, v8
	v_lshlrev_b32_e32 v64, 16, v5
	v_and_b32_e32 v65, 0xffff0000, v5
	v_lshlrev_b32_e32 v80, 16, v9
	v_and_b32_e32 v81, 0xffff0000, v9
	v_lshlrev_b32_e32 v66, 16, v6
	v_and_b32_e32 v67, 0xffff0000, v6
	v_lshlrev_b32_e32 v82, 16, v10
	v_and_b32_e32 v83, 0xffff0000, v10
	v_lshlrev_b32_e32 v68, 16, v7
	v_and_b32_e32 v69, 0xffff0000, v7
	v_lshlrev_b32_e32 v84, 16, v11
	v_and_b32_e32 v85, 0xffff0000, v11
	v_add_f32_e32 v54, 1.0, v54
	v_add_f32_e32 v55, 1.0, v55
	v_add_f32_e32 v56, 1.0, v56
	v_add_f32_e32 v57, 1.0, v57
	v_add_f32_e32 v58, 1.0, v58
	v_add_f32_e32 v59, 1.0, v59
	v_add_f32_e32 v60, 1.0, v60
	v_add_f32_e32 v61, 1.0, v61
	v_rcp_f32_e32 v54, v54
	v_rcp_f32_e32 v55, v55
	v_rcp_f32_e32 v56, v56
	v_rcp_f32_e32 v57, v57
	v_rcp_f32_e32 v58, v58
	v_rcp_f32_e32 v59, v59
	v_rcp_f32_e32 v60, v60
	v_rcp_f32_e32 v61, v61
	v_pk_add_f32 v[62:63], v[62:63], v[78:79]
	v_pk_add_f32 v[64:65], v[64:65], v[80:81]
	v_pk_add_f32 v[66:67], v[66:67], v[82:83]
	v_pk_add_f32 v[68:69], v[68:69], v[84:85]
	v_pk_mul_f32 v[54:55], v[54:55], v[46:47]
	v_pk_mul_f32 v[56:57], v[56:57], v[48:49]
	v_pk_mul_f32 v[58:59], v[58:59], v[50:51]
	v_pk_mul_f32 v[60:61], v[60:61], v[52:53]
	v_pk_mul_f32 v[62:63], v[62:63], v[54:55]
	v_pk_mul_f32 v[64:65], v[64:65], v[56:57]
	v_pk_mul_f32 v[66:67], v[66:67], v[58:59]
	v_pk_mul_f32 v[68:69], v[68:69], v[60:61]
	v_pk_mul_f32 v[46:47], v[62:63], v[62:63]
	v_pk_mul_f32 v[48:49], v[66:67], v[66:67]
	v_pk_fma_f32 v[46:47], v[64:65], v[64:65], v[46:47]
	v_pk_fma_f32 v[48:49], v[68:69], v[68:69], v[48:49]
	v_pk_add_f32 v[46:47], v[46:47], v[48:49]
	s_nop 0
	v_add_f32_e32 v46, v46, v47
	s_nop 1
	v_add_f32_dpp v46, v46, v46 quad_perm:[1,0,3,2] row_mask:0xf bank_mask:0xf
	s_nop 1
	v_add_f32_dpp v46, v46, v46 quad_perm:[2,3,0,1] row_mask:0xf bank_mask:0xf
	s_nop 1
	v_add_f32_dpp v46, v46, v46 row_half_mirror row_mask:0xf bank_mask:0xf
	s_nop 1
	v_add_f32_dpp v46, v46, v46 row_mirror row_mask:0xf bank_mask:0xf
	s_nop 1
	ds_swizzle_b32 v47, v46 offset:swizzle(SWAP,16)
	s_waitcnt lgkmcnt(0)
	v_add_f32_e32 v46, v46, v47
	v_fmamk_f32 v46, v46, 0x3b800000, v174
	v_rsq_f32_e32 v46, v46
	s_nop 0
	v_pk_mul_f32 v[62:63], v[62:63], v[46:47] op_sel_hi:[1,0]
	v_pk_mul_f32 v[64:65], v[64:65], v[46:47] op_sel_hi:[1,0]
	v_pk_mul_f32 v[66:67], v[66:67], v[46:47] op_sel_hi:[1,0]
	v_pk_mul_f32 v[68:69], v[68:69], v[46:47] op_sel_hi:[1,0]
	v_pk_mul_f32 v[62:63], v[62:63], v[36:37]
	v_pk_mul_f32 v[64:65], v[64:65], v[38:39]
	v_pk_mul_f32 v[66:67], v[66:67], v[40:41]
	v_pk_mul_f32 v[68:69], v[68:69], v[42:43]
	v_cvt_pk_bf16_f32 v88, v62, v63
	v_cvt_pk_bf16_f32 v89, v64, v65
	v_cvt_pk_bf16_f32 v90, v66, v67
	v_cvt_pk_bf16_f32 v91, v68, v69
	global_load_dwordx4 v[4:7], v100, s[4:5] nt
	global_load_dwordx4 v[8:11], v100, s[6:7] nt
	global_load_dwordx4 v[12:15], v100, vcc
	s_add_u32 s4, s4, s16
	s_addc_u32 s5, s5, 0
	s_add_u32 s6, s6, s16
	s_addc_u32 s7, s7, 0
	s_add_u32 vcc_lo, vcc_lo, s16
	s_addc_u32 vcc_hi, vcc_hi, 0
	global_store_dwordx4 v100, v[88:91], s[8:9]
	s_add_u32 s8, s8, s16
	s_addc_u32 s9, s9, 0
	s_add_u32 s18, s18, s28
	s_cmp_lt_u32 s18, s35
	s_cbranch_scc0 .Lc_exit
	s_waitcnt vmcnt(9)
	v_lshlrev_b32_e32 v46, 16, v28
	v_and_b32_e32 v47, 0xffff0000, v28
	v_lshlrev_b32_e32 v48, 16, v29
	v_and_b32_e32 v49, 0xffff0000, v29
	v_lshlrev_b32_e32 v50, 16, v30
	v_and_b32_e32 v51, 0xffff0000, v30
	v_lshlrev_b32_e32 v52, 16, v31
	v_and_b32_e32 v53, 0xffff0000, v31
	v_mul_f32_e32 v54, 0xbfb8aa3b, v46
	v_mul_f32_e32 v55, 0xbfb8aa3b, v47
	v_mul_f32_e32 v56, 0xbfb8aa3b, v48
	v_mul_f32_e32 v57, 0xbfb8aa3b, v49
	v_mul_f32_e32 v58, 0xbfb8aa3b, v50
	v_mul_f32_e32 v59, 0xbfb8aa3b, v51
	v_mul_f32_e32 v60, 0xbfb8aa3b, v52
	v_mul_f32_e32 v61, 0xbfb8aa3b, v53
	v_exp_f32_e32 v54, v54
	v_exp_f32_e32 v55, v55
	v_exp_f32_e32 v56, v56
	v_exp_f32_e32 v57, v57
	v_exp_f32_e32 v58, v58
	v_exp_f32_e32 v59, v59
	v_exp_f32_e32 v60, v60
	v_exp_f32_e32 v61, v61
	v_lshlrev_b32_e32 v62, 16, v20
	v_and_b32_e32 v63, 0xffff0000, v20
	v_lshlrev_b32_e32 v78, 16, v24
	v_and_b32_e32 v79, 0xffff0000, v24
	v_lshlrev_b32_e32 v64, 16, v21
	v_and_b32_e32 v65, 0xffff0000, v21
	v_lshlrev_b32_e32 v80, 16, v25
	v_and_b32_e32 v81, 0xffff0000, v25
	v_lshlrev_b32_e32 v66, 16, v22
	v_and_b32_e32 v67, 0xffff0000, v22
	v_lshlrev_b32_e32 v82, 16, v26
	v_and_b32_e32 v83, 0xffff0000, v26
	v_lshlrev_b32_e32 v68, 16, v23
	v_and_b32_e32 v69, 0xffff0000, v23
	v_lshlrev_b32_e32 v84, 16, v27
	v_and_b32_e32 v85, 0xffff0000, v27
	v_add_f32_e32 v54, 1.0, v54
	v_add_f32_e32 v55, 1.0, v55
	v_add_f32_e32 v56, 1.0, v56
	v_add_f32_e32 v57, 1.0, v57
	v_add_f32_e32 v58, 1.0, v58
	v_add_f32_e32 v59, 1.0, v59
	v_add_f32_e32 v60, 1.0, v60
	v_add_f32_e32 v61, 1.0, v61
	v_rcp_f32_e32 v54, v54
	v_rcp_f32_e32 v55, v55
	v_rcp_f32_e32 v56, v56
	v_rcp_f32_e32 v57, v57
	v_rcp_f32_e32 v58, v58
	v_rcp_f32_e32 v59, v59
	v_rcp_f32_e32 v60, v60
	v_rcp_f32_e32 v61, v61
	v_pk_add_f32 v[62:63], v[62:63], v[78:79]
	v_pk_add_f32 v[64:65], v[64:65], v[80:81]
	v_pk_add_f32 v[66:67], v[66:67], v[82:83]
	v_pk_add_f32 v[68:69], v[68:69], v[84:85]
	v_pk_mul_f32 v[54:55], v[54:55], v[46:47]
	v_pk_mul_f32 v[56:57], v[56:57], v[48:49]
	v_pk_mul_f32 v[58:59], v[58:59], v[50:51]
	v_pk_mul_f32 v[60:61], v[60:61], v[52:53]
	v_pk_mul_f32 v[62:63], v[62:63], v[54:55]
	v_pk_mul_f32 v[64:65], v[64:65], v[56:57]
	v_pk_mul_f32 v[66:67], v[66:67], v[58:59]
	v_pk_mul_f32 v[68:69], v[68:69], v[60:61]
	v_pk_mul_f32 v[46:47], v[62:63], v[62:63]
	v_pk_mul_f32 v[48:49], v[66:67], v[66:67]
	v_pk_fma_f32 v[46:47], v[64:65], v[64:65], v[46:47]
	v_pk_fma_f32 v[48:49], v[68:69], v[68:69], v[48:49]
	v_pk_add_f32 v[46:47], v[46:47], v[48:49]
	s_nop 0
	v_add_f32_e32 v46, v46, v47
	s_nop 1
	v_add_f32_dpp v46, v46, v46 quad_perm:[1,0,3,2] row_mask:0xf bank_mask:0xf
	s_nop 1
	v_add_f32_dpp v46, v46, v46 quad_perm:[2,3,0,1] row_mask:0xf bank_mask:0xf
	s_nop 1
	v_add_f32_dpp v46, v46, v46 row_half_mirror row_mask:0xf bank_mask:0xf
	s_nop 1
	v_add_f32_dpp v46, v46, v46 row_mirror row_mask:0xf bank_mask:0xf
	s_nop 1
	ds_swizzle_b32 v47, v46 offset:swizzle(SWAP,16)
	s_waitcnt lgkmcnt(0)
	v_add_f32_e32 v46, v46, v47
	v_fmamk_f32 v46, v46, 0x3b800000, v174
	v_rsq_f32_e32 v46, v46
	s_nop 0
	v_pk_mul_f32 v[62:63], v[62:63], v[46:47] op_sel_hi:[1,0]
	v_pk_mul_f32 v[64:65], v[64:65], v[46:47] op_sel_hi:[1,0]
	v_pk_mul_f32 v[66:67], v[66:67], v[46:47] op_sel_hi:[1,0]
	v_pk_mul_f32 v[68:69], v[68:69], v[46:47] op_sel_hi:[1,0]
	v_pk_mul_f32 v[62:63], v[62:63], v[36:37]
	v_pk_mul_f32 v[64:65], v[64:65], v[38:39]
	v_pk_mul_f32 v[66:67], v[66:67], v[40:41]
	v_pk_mul_f32 v[68:69], v[68:69], v[42:43]
	v_cvt_pk_bf16_f32 v88, v62, v63
	v_cvt_pk_bf16_f32 v89, v64, v65
	v_cvt_pk_bf16_f32 v90, v66, v67
	v_cvt_pk_bf16_f32 v91, v68, v69
	global_load_dwordx4 v[20:23], v100, s[4:5] nt
	global_load_dwordx4 v[24:27], v100, s[6:7] nt
	global_load_dwordx4 v[28:31], v100, vcc
	s_add_u32 s4, s4, s16
	s_addc_u32 s5, s5, 0
	s_add_u32 s6, s6, s16
	s_addc_u32 s7, s7, 0
	s_add_u32 vcc_lo, vcc_lo, s16
	s_addc_u32 vcc_hi, vcc_hi, 0
	global_store_dwordx4 v100, v[88:91], s[8:9]
	s_add_u32 s8, s8, s16
	s_addc_u32 s9, s9, 0
	s_add_u32 s18, s18, s28
	s_cmp_lt_u32 s18, s35
	s_cbranch_scc0 .Lc_exit
	s_waitcnt vmcnt(9)
	v_lshlrev_b32_e32 v46, 16, v124
	v_and_b32_e32 v47, 0xffff0000, v124
	v_lshlrev_b32_e32 v48, 16, v125
	v_and_b32_e32 v49, 0xffff0000, v125
	v_lshlrev_b32_e32 v50, 16, v126
	v_and_b32_e32 v51, 0xffff0000, v126
	v_lshlrev_b32_e32 v52, 16, v127
	v_and_b32_e32 v53, 0xffff0000, v127
	v_mul_f32_e32 v54, 0xbfb8aa3b, v46
	v_mul_f32_e32 v55, 0xbfb8aa3b, v47
	v_mul_f32_e32 v56, 0xbfb8aa3b, v48
	v_mul_f32_e32 v57, 0xbfb8aa3b, v49
	v_mul_f32_e32 v58, 0xbfb8aa3b, v50
	v_mul_f32_e32 v59, 0xbfb8aa3b, v51
	v_mul_f32_e32 v60, 0xbfb8aa3b, v52
	v_mul_f32_e32 v61, 0xbfb8aa3b, v53
	v_exp_f32_e32 v54, v54
	v_exp_f32_e32 v55, v55
	v_exp_f32_e32 v56, v56
	v_exp_f32_e32 v57, v57
	v_exp_f32_e32 v58, v58
	v_exp_f32_e32 v59, v59
	v_exp_f32_e32 v60, v60
	v_exp_f32_e32 v61, v61
	v_lshlrev_b32_e32 v62, 16, v116
	v_and_b32_e32 v63, 0xffff0000, v116
	v_lshlrev_b32_e32 v78, 16, v120
	v_and_b32_e32 v79, 0xffff0000, v120
	v_lshlrev_b32_e32 v64, 16, v117
	v_and_b32_e32 v65, 0xffff0000, v117
	v_lshlrev_b32_e32 v80, 16, v121
	v_and_b32_e32 v81, 0xffff0000, v121
	v_lshlrev_b32_e32 v66, 16, v118
	v_and_b32_e32 v67, 0xffff0000, v118
	v_lshlrev_b32_e32 v82, 16, v122
	v_and_b32_e32 v83, 0xffff0000, v122
	v_lshlrev_b32_e32 v68, 16, v119
	v_and_b32_e32 v69, 0xffff0000, v119
	v_lshlrev_b32_e32 v84, 16, v123
	v_and_b32_e32 v85, 0xffff0000, v123
	v_add_f32_e32 v54, 1.0, v54
	v_add_f32_e32 v55, 1.0, v55
	v_add_f32_e32 v56, 1.0, v56
	v_add_f32_e32 v57, 1.0, v57
	v_add_f32_e32 v58, 1.0, v58
	v_add_f32_e32 v59, 1.0, v59
	v_add_f32_e32 v60, 1.0, v60
	v_add_f32_e32 v61, 1.0, v61
	v_rcp_f32_e32 v54, v54
	v_rcp_f32_e32 v55, v55
	v_rcp_f32_e32 v56, v56
	v_rcp_f32_e32 v57, v57
	v_rcp_f32_e32 v58, v58
	v_rcp_f32_e32 v59, v59
	v_rcp_f32_e32 v60, v60
	v_rcp_f32_e32 v61, v61
	v_pk_add_f32 v[62:63], v[62:63], v[78:79]
	v_pk_add_f32 v[64:65], v[64:65], v[80:81]
	v_pk_add_f32 v[66:67], v[66:67], v[82:83]
	v_pk_add_f32 v[68:69], v[68:69], v[84:85]
	v_pk_mul_f32 v[54:55], v[54:55], v[46:47]
	v_pk_mul_f32 v[56:57], v[56:57], v[48:49]
	v_pk_mul_f32 v[58:59], v[58:59], v[50:51]
	v_pk_mul_f32 v[60:61], v[60:61], v[52:53]
	v_pk_mul_f32 v[62:63], v[62:63], v[54:55]
	v_pk_mul_f32 v[64:65], v[64:65], v[56:57]
	v_pk_mul_f32 v[66:67], v[66:67], v[58:59]
	v_pk_mul_f32 v[68:69], v[68:69], v[60:61]
	v_pk_mul_f32 v[46:47], v[62:63], v[62:63]
	v_pk_mul_f32 v[48:49], v[66:67], v[66:67]
	v_pk_fma_f32 v[46:47], v[64:65], v[64:65], v[46:47]
	v_pk_fma_f32 v[48:49], v[68:69], v[68:69], v[48:49]
	v_pk_add_f32 v[46:47], v[46:47], v[48:49]
	s_nop 0
	v_add_f32_e32 v46, v46, v47
	s_nop 1
	v_add_f32_dpp v46, v46, v46 quad_perm:[1,0,3,2] row_mask:0xf bank_mask:0xf
	s_nop 1
	v_add_f32_dpp v46, v46, v46 quad_perm:[2,3,0,1] row_mask:0xf bank_mask:0xf
	s_nop 1
	v_add_f32_dpp v46, v46, v46 row_half_mirror row_mask:0xf bank_mask:0xf
	s_nop 1
	v_add_f32_dpp v46, v46, v46 row_mirror row_mask:0xf bank_mask:0xf
	s_nop 1
	ds_swizzle_b32 v47, v46 offset:swizzle(SWAP,16)
	s_waitcnt lgkmcnt(0)
	v_add_f32_e32 v46, v46, v47
	v_fmamk_f32 v46, v46, 0x3b800000, v174
	v_rsq_f32_e32 v46, v46
	s_nop 0
	v_pk_mul_f32 v[62:63], v[62:63], v[46:47] op_sel_hi:[1,0]
	v_pk_mul_f32 v[64:65], v[64:65], v[46:47] op_sel_hi:[1,0]
	v_pk_mul_f32 v[66:67], v[66:67], v[46:47] op_sel_hi:[1,0]
	v_pk_mul_f32 v[68:69], v[68:69], v[46:47] op_sel_hi:[1,0]
	v_pk_mul_f32 v[62:63], v[62:63], v[36:37]
	v_pk_mul_f32 v[64:65], v[64:65], v[38:39]
	v_pk_mul_f32 v[66:67], v[66:67], v[40:41]
	v_pk_mul_f32 v[68:69], v[68:69], v[42:43]
	v_cvt_pk_bf16_f32 v88, v62, v63
	v_cvt_pk_bf16_f32 v89, v64, v65
	v_cvt_pk_bf16_f32 v90, v66, v67
	v_cvt_pk_bf16_f32 v91, v68, v69
	global_load_dwordx4 v[116:119], v100, s[4:5] nt
	global_load_dwordx4 v[120:123], v100, s[6:7] nt
	global_load_dwordx4 v[124:127], v100, vcc
	s_add_u32 s4, s4, s16
	s_addc_u32 s5, s5, 0
	s_add_u32 s6, s6, s16
	s_addc_u32 s7, s7, 0
	s_add_u32 vcc_lo, vcc_lo, s16
	s_addc_u32 vcc_hi, vcc_hi, 0
	global_store_dwordx4 v100, v[88:91], s[8:9]
	s_add_u32 s8, s8, s16
	s_addc_u32 s9, s9, 0
	s_add_u32 s18, s18, s28
	s_cmp_lt_u32 s18, s35
	s_cbranch_scc0 .Lc_exit
	s_branch .Lc_loop

.LBB0_800:
	s_mov_b64 exec, -1
	s_lshl_b32 s4, s86, 4
	s_add_u32 s4, s60, s4
	s_addc_u32 s5, s61, 0
	s_load_dwordx4 s[8:11], s[4:5], 0xc0
	v_readlane_b32 s6, v253, 3
	s_waitcnt vmcnt(0)
	s_waitcnt lgkmcnt(0)
	s_cmp_eq_u32 s8, 0
	s_cbranch_scc0 .Ldf_done
	s_cmp_eq_u32 s10, 4
	s_cbranch_scc0 .Ldf_done
	s_cmp_lt_u32 s9, 3
	s_cbranch_scc0 .Ldf_done
	s_movk_i32 s7, 0xb58
